# row statistics of the SwiGLU epilogues staged through LDS by a DMA at unit start (phases 1 and 8), no vmcnt(0) wait in the epilogue
# speedup vs baseline: 1.0028x; 1.0027x over previous
.LBB0_169:
	s_ashr_i32 s15, s14, 31
	s_lshl_b64 s[16:17], s[14:15], 19
	s_add_u32 s16, s80, s16
	s_addc_u32 s17, s81, s17
	s_and_b64 s[18:19], s[2:3], exec
	s_cselect_b32 s15, s17, s31
	s_cselect_b32 s69, s16, s30
	s_ashr_i32 s13, s12, 31
	s_lshl_b64 s[18:19], s[12:13], 19
	s_add_u32 s18, s22, s18
	s_addc_u32 s19, s23, s19
	s_and_b64 s[52:53], s[2:3], exec
	s_cselect_b32 s13, s19, s29
	s_cselect_b32 s70, s18, s28
	s_cmp_ge_u32 s21, 0x1000
	s_cbranch_scc1 .Lst1_skip
	s_lshl_b32 s52, s20, 12
	s_add_u32 s52, s6, s52
	s_addc_u32 s53, s7, 0
	s_and_b32 s71, s55, 1
	s_lshl_b32 s71, s71, 12
	s_add_i32 s71, s71, 0x20000
	s_add_i32 m0, s21, s71
	v_lshlrev_b32_e32 v202, 4, v0
	s_nop 0
	global_load_lds_dwordx4 v202, s[52:53]
.Lst1_skip:
	s_add_u32 s52, s30, 0x40080
	s_addc_u32 s53, s31, 0
	s_add_u32 s71, s28, 0x100
	v_mov_b32_e32 v2, 0
	v_mov_b32_e32 v3, 0
	v_mov_b64_e32 v[4:5], v[2:3]
	v_mov_b64_e32 v[6:7], v[2:3]
	v_mov_b64_e32 v[8:9], v[2:3]
	v_mov_b64_e32 v[10:11], v[2:3]
	v_mov_b64_e32 v[12:13], v[2:3]
	v_mov_b64_e32 v[14:15], v[2:3]
	v_mov_b64_e32 v[16:17], v[2:3]
	v_mov_b64_e32 v[18:19], v[2:3]
	v_mov_b64_e32 v[20:21], v[2:3]
	v_mov_b64_e32 v[22:23], v[2:3]
	v_mov_b64_e32 v[24:25], v[2:3]
	v_mov_b64_e32 v[26:27], v[2:3]
	v_mov_b64_e32 v[28:29], v[2:3]
	v_mov_b64_e32 v[30:31], v[2:3]
	v_mov_b64_e32 v[32:33], v[2:3]
	v_mov_b64_e32 v[34:35], v[2:3]
	v_mov_b64_e32 v[36:37], v[2:3]
	v_mov_b64_e32 v[38:39], v[2:3]
	v_mov_b64_e32 v[40:41], v[2:3]
	v_mov_b64_e32 v[42:43], v[2:3]
	v_mov_b64_e32 v[44:45], v[2:3]
	v_mov_b64_e32 v[46:47], v[2:3]
	v_mov_b64_e32 v[48:49], v[2:3]
	v_mov_b64_e32 v[50:51], v[2:3]
	v_mov_b64_e32 v[52:53], v[2:3]
	v_mov_b64_e32 v[54:55], v[2:3]
	v_mov_b64_e32 v[56:57], v[2:3]
	v_mov_b64_e32 v[58:59], v[2:3]
	v_mov_b64_e32 v[60:61], v[2:3]
	v_mov_b64_e32 v[62:63], v[2:3]
	v_mov_b64_e32 v[64:65], v[2:3]
	v_mov_b64_e32 v[66:67], v[2:3]
	v_mov_b64_e32 v[68:69], v[2:3]
	v_mov_b64_e32 v[70:71], v[2:3]
	v_mov_b64_e32 v[72:73], v[2:3]
	v_mov_b64_e32 v[74:75], v[2:3]
	v_mov_b64_e32 v[76:77], v[2:3]
	v_mov_b64_e32 v[78:79], v[2:3]
	v_mov_b64_e32 v[80:81], v[2:3]
	v_mov_b64_e32 v[82:83], v[2:3]
	v_mov_b64_e32 v[84:85], v[2:3]
	v_mov_b64_e32 v[86:87], v[2:3]
	v_mov_b64_e32 v[88:89], v[2:3]
	v_mov_b64_e32 v[90:91], v[2:3]
	v_mov_b64_e32 v[92:93], v[2:3]
	v_mov_b64_e32 v[94:95], v[2:3]
	v_mov_b64_e32 v[96:97], v[2:3]
	v_mov_b64_e32 v[98:99], v[2:3]
	v_mov_b64_e32 v[100:101], v[2:3]
	v_mov_b64_e32 v[102:103], v[2:3]
	v_mov_b64_e32 v[104:105], v[2:3]
	v_mov_b64_e32 v[106:107], v[2:3]
	v_mov_b64_e32 v[108:109], v[2:3]
	v_mov_b64_e32 v[110:111], v[2:3]
	v_mov_b64_e32 v[112:113], v[2:3]
	v_mov_b64_e32 v[114:115], v[2:3]
	v_mov_b64_e32 v[116:117], v[2:3]
	v_mov_b64_e32 v[118:119], v[2:3]
	v_mov_b64_e32 v[120:121], v[2:3]
	v_mov_b64_e32 v[122:123], v[2:3]
	v_mov_b64_e32 v[124:125], v[2:3]
	v_mov_b64_e32 v[126:127], v[2:3]
	v_mov_b64_e32 v[128:129], v[2:3]
	s_addc_u32 s72, s29, 0
	s_mov_b32 s73, -2
	s_waitcnt lgkmcnt(0)

.LBB0_173:
	v_lshl_add_u32 v202, s20, 8, v1
	s_and_b32 s71, s55, 1
	s_lshl_b32 s71, s71, 12
	s_add_i32 s71, s71, 0x20000
	v_lshl_add_u32 v206, v1, 4, s71
	v_or_b32_e32 v162, 16, v202
	v_ashrrev_i32_e32 v203, 31, v202
	v_ashrrev_i32_e32 v163, 31, v162
	v_or_b32_e32 v160, 32, v202
	v_or_b32_e32 v158, 48, v202
	v_ashrrev_i32_e32 v161, 31, v160
	v_ashrrev_i32_e32 v159, 31, v158
	v_add_u32_e32 v156, 0x80, v202
	v_add_u32_e32 v154, 0x90, v202
	ds_read_b128 v[170:173], v206
	ds_read_b128 v[174:177], v206 offset:256
	v_ashrrev_i32_e32 v157, 31, v156
	v_ashrrev_i32_e32 v155, 31, v154
	ds_read_b128 v[178:181], v206 offset:512
	ds_read_b128 v[182:185], v206 offset:768
	ds_read_b128 v[186:189], v206 offset:2048
	ds_read_b128 v[190:193], v206 offset:2304
	v_add_u32_e32 v150, 0xa0, v202
	v_ashrrev_i32_e32 v151, 31, v150
	ds_read_b128 v[194:197], v206 offset:2560
	v_add_u32_e32 v148, 0xb0, v202
	v_ashrrev_i32_e32 v149, 31, v148
	ds_read_b128 v[198:201], v206 offset:2816
	v_pk_mul_f32 v[124:125], v[128:129], v[124:125]
	v_pk_mul_f32 v[122:123], v[126:127], v[122:123]
	v_pk_mul_f32 v[116:117], v[120:121], v[116:117]
	v_lshl_or_b32 v204, s68, 7, v164
	v_pk_mul_f32 v[114:115], v[118:119], v[114:115]
	v_ashrrev_i32_e32 v205, 31, v204
	v_pk_mul_f32 v[108:109], v[112:113], v[108:109]
	v_pk_mul_f32 v[106:107], v[110:111], v[106:107]
	v_pk_mul_f32 v[100:101], v[104:105], v[100:101]
	v_pk_mul_f32 v[98:99], v[102:103], v[98:99]
	v_pk_mul_f32 v[92:93], v[96:97], v[92:93]
	v_pk_mul_f32 v[90:91], v[94:95], v[90:91]
	v_pk_mul_f32 v[84:85], v[88:89], v[84:85]
	v_pk_mul_f32 v[82:83], v[86:87], v[82:83]
	v_pk_mul_f32 v[76:77], v[80:81], v[76:77]
	v_pk_mul_f32 v[74:75], v[78:79], v[74:75]
	v_pk_mul_f32 v[68:69], v[72:73], v[68:69]
	v_pk_mul_f32 v[66:67], v[70:71], v[66:67]
	v_pk_mul_f32 v[60:61], v[64:65], v[60:61]
	v_pk_mul_f32 v[58:59], v[62:63], v[58:59]
	v_pk_mul_f32 v[52:53], v[56:57], v[52:53]
	v_pk_mul_f32 v[50:51], v[54:55], v[50:51]
	v_pk_mul_f32 v[44:45], v[48:49], v[44:45]
	v_pk_mul_f32 v[42:43], v[46:47], v[42:43]
	v_pk_mul_f32 v[36:37], v[40:41], v[36:37]
	v_pk_mul_f32 v[34:35], v[38:39], v[34:35]
	v_pk_mul_f32 v[28:29], v[32:33], v[28:29]
	v_pk_mul_f32 v[26:27], v[30:31], v[26:27]
	v_pk_mul_f32 v[20:21], v[24:25], v[20:21]
	v_pk_mul_f32 v[18:19], v[22:23], v[18:19]
	v_pk_mul_f32 v[12:13], v[16:17], v[12:13]
	v_pk_mul_f32 v[10:11], v[14:15], v[10:11]
	v_pk_mul_f32 v[4:5], v[8:9], v[4:5]
	v_pk_mul_f32 v[2:3], v[6:7], v[2:3]
	s_andn2_b64 vcc, exec, s[2:3]
	s_mov_b64 s[2:3], -1
	v_readlane_b32 s70, v253, 14
	v_readlane_b32 s71, v253, 15
	s_waitcnt lgkmcnt(0)
	v_mov_b32_e32 v152, v171
	v_mov_b32_e32 v153, v172
	v_mov_b32_e32 v171, v173
	v_pk_add_f32 v[152:153], v[152:153], v[170:171]
	v_mov_b32_e32 v170, v175
	v_add_f32_e32 v149, v152, v153
	v_fmamk_f32 v149, v149, 0x3a800000, v168
	v_mov_b32_e32 v171, v176
	v_mov_b32_e32 v175, v177
	v_mov_b32_e32 v172, v179
	v_mov_b32_e32 v173, v180
	v_mov_b32_e32 v179, v181
	v_mov_b32_e32 v176, v183
	v_mov_b32_e32 v177, v184
	v_mov_b32_e32 v183, v185
	v_mov_b32_e32 v180, v187
	v_mov_b32_e32 v181, v188
	v_mov_b32_e32 v187, v189
	v_mov_b32_e32 v184, v191
	v_mov_b32_e32 v185, v192
	v_mov_b32_e32 v191, v193
	v_mov_b32_e32 v188, v195
	v_mov_b32_e32 v189, v196
	v_mov_b32_e32 v195, v197
	v_rsq_f32_e32 v163, v149
	v_mov_b32_e32 v192, v199
	v_mov_b32_e32 v193, v200
	v_mov_b32_e32 v199, v201
	v_pk_add_f32 v[152:153], v[170:171], v[174:175]
	v_pk_add_f32 v[170:171], v[172:173], v[178:179]
	v_pk_add_f32 v[172:173], v[176:177], v[182:183]
	v_pk_add_f32 v[174:175], v[180:181], v[186:187]
	v_pk_add_f32 v[176:177], v[184:185], v[190:191]
	v_pk_add_f32 v[178:179], v[188:189], v[194:195]
	v_pk_add_f32 v[180:181], v[192:193], v[198:199]
	v_add_f32_e32 v151, v152, v153
	v_add_f32_e32 v152, v170, v171
	v_add_f32_e32 v153, v172, v173
	v_add_f32_e32 v155, v174, v175
	v_add_f32_e32 v157, v176, v177
	v_add_f32_e32 v159, v178, v179
	v_add_f32_e32 v161, v180, v181
	v_fmamk_f32 v149, v151, 0x3a800000, v168
	v_fmamk_f32 v151, v152, 0x3a800000, v168
	v_fmamk_f32 v152, v153, 0x3a800000, v168
	v_fmamk_f32 v153, v155, 0x3a800000, v168
	v_fmamk_f32 v155, v157, 0x3a800000, v168
	v_fmamk_f32 v157, v159, 0x3a800000, v168
	v_fmamk_f32 v159, v161, 0x3a800000, v168
	v_rsq_f32_e32 v169, v151
	v_rsq_f32_e32 v151, v157
	v_mul_f32_e32 v157, 0xbfb8aa3b, v163
	v_rsq_f32_e32 v161, v149
	v_rsq_f32_e32 v149, v159
	v_mul_f32_e32 v159, v126, v157
	v_exp_f32_e32 v159, v159
	v_mul_f32_e32 v172, v127, v157
	v_exp_f32_e32 v175, v172
	v_mul_f32_e32 v172, v163, v163
	v_add_f32_e32 v159, 1.0, v159
	v_rcp_f32_e32 v174, v159
	v_add_f32_e32 v159, 1.0, v175
	v_rcp_f32_e32 v175, v159
	v_mul_f32_e32 v159, v128, v157
	v_mul_f32_e32 v163, v129, v157
	v_exp_f32_e32 v159, v159
	v_exp_f32_e32 v163, v163
	v_rsq_f32_e32 v173, v152
	v_rsq_f32_e32 v176, v153
	v_add_f32_e32 v128, 1.0, v159
	v_add_f32_e32 v129, 1.0, v163
	v_rcp_f32_e32 v128, v128
	v_rcp_f32_e32 v129, v129
	v_pk_mul_f32 v[126:127], v[172:173], v[174:175] op_sel_hi:[0,1]
	v_pk_mul_f32 v[122:123], v[122:123], v[126:127]
	v_mov_b64_e32 v[152:153], s[4:5]
	v_pk_mul_f32 v[126:127], v[172:173], v[128:129] op_sel_hi:[0,1]
	v_mul_f32_e32 v128, v118, v157
	v_mul_f32_e32 v129, v119, v157
	v_exp_f32_e32 v128, v128
	v_exp_f32_e32 v129, v129
	v_pk_mul_f32 v[124:125], v[124:125], v[126:127]
	v_mad_i64_i32 v[170:171], s[28:29], v202, s67, v[152:153]
	v_add_f32_e32 v126, 1.0, v128
	v_add_f32_e32 v127, 1.0, v129
	v_mul_f32_e32 v128, v120, v157
	v_mul_f32_e32 v129, v121, v157
	v_exp_f32_e32 v128, v128
	v_exp_f32_e32 v129, v129
	v_rcp_f32_e32 v126, v126
	v_rcp_f32_e32 v127, v127
	v_add_f32_e32 v120, 1.0, v128
	v_add_f32_e32 v121, 1.0, v129
	v_rcp_f32_e32 v120, v120
	v_rcp_f32_e32 v121, v121
	v_pk_mul_f32 v[118:119], v[172:173], v[126:127] op_sel_hi:[0,1]
	v_pk_mul_f32 v[118:119], v[114:115], v[118:119]
	v_rsq_f32_e32 v155, v155
	v_pk_mul_f32 v[114:115], v[172:173], v[120:121] op_sel_hi:[0,1]
	v_pk_mul_f32 v[120:121], v[116:117], v[114:115]
	v_lshlrev_b64 v[114:115], 1, v[204:205]
	v_lshl_add_u64 v[126:127], v[170:171], 0, v[114:115]
	v_cvt_pk_bf16_f32 v116, v122, v123
	v_cvt_pk_bf16_f32 v117, v124, v125
	v_cvt_pk_bf16_f32 v118, v118, v119
	v_cvt_pk_bf16_f32 v119, v120, v121
	global_store_dwordx4 v[126:127], v[116:119], off
	s_nop 1
	v_mul_f32_e32 v119, 0xbfb8aa3b, v161
	v_mul_f32_e32 v118, v110, v119
	v_exp_f32_e32 v120, v118
	v_mul_f32_e32 v118, v111, v119
	v_exp_f32_e32 v121, v118
	v_mul_f32_e32 v122, v112, v119
	v_mul_f32_e32 v123, v113, v119
	v_exp_f32_e32 v122, v122
	v_exp_f32_e32 v123, v123
	v_add_f32_e32 v120, 1.0, v120
	v_add_f32_e32 v121, 1.0, v121
	v_rcp_f32_e32 v120, v120
	v_rcp_f32_e32 v121, v121
	v_add_f32_e32 v112, 1.0, v122
	v_add_f32_e32 v113, 1.0, v123
	v_rcp_f32_e32 v112, v112
	v_rcp_f32_e32 v113, v113
	v_mul_f32_e32 v118, v161, v161
	v_pk_mul_f32 v[110:111], v[118:119], v[120:121] op_sel_hi:[0,1]
	v_pk_mul_f32 v[106:107], v[106:107], v[110:111]
	v_pk_mul_f32 v[110:111], v[118:119], v[112:113] op_sel_hi:[0,1]
	v_mul_f32_e32 v112, v102, v119
	v_mul_f32_e32 v113, v103, v119
	v_exp_f32_e32 v112, v112
	v_exp_f32_e32 v113, v113
	v_pk_mul_f32 v[108:109], v[108:109], v[110:111]
	v_mad_i64_i32 v[116:117], s[28:29], v162, s67, v[152:153]
	v_add_f32_e32 v110, 1.0, v112
	v_add_f32_e32 v111, 1.0, v113
	v_mul_f32_e32 v112, v104, v119
	v_mul_f32_e32 v113, v105, v119
	v_exp_f32_e32 v112, v112
	v_exp_f32_e32 v113, v113
	v_rcp_f32_e32 v110, v110
	v_rcp_f32_e32 v111, v111
	v_add_f32_e32 v104, 1.0, v112
	v_add_f32_e32 v105, 1.0, v113
	v_rcp_f32_e32 v104, v104
	v_rcp_f32_e32 v105, v105
	v_pk_mul_f32 v[102:103], v[118:119], v[110:111] op_sel_hi:[0,1]
	v_pk_mul_f32 v[102:103], v[98:99], v[102:103]
	v_lshl_add_u64 v[110:111], v[116:117], 0, v[114:115]
	v_pk_mul_f32 v[98:99], v[118:119], v[104:105] op_sel_hi:[0,1]
	v_pk_mul_f32 v[104:105], v[100:101], v[98:99]
	v_cvt_pk_bf16_f32 v98, v106, v107
	v_cvt_pk_bf16_f32 v99, v108, v109
	v_cvt_pk_bf16_f32 v100, v102, v103
	v_cvt_pk_bf16_f32 v101, v104, v105
	global_store_dwordx4 v[110:111], v[98:101], off
	s_nop 1
	v_mul_f32_e32 v101, 0xbfb8aa3b, v169
	v_mul_f32_e32 v100, v94, v101
	v_exp_f32_e32 v102, v100
	v_mul_f32_e32 v100, v95, v101
	v_exp_f32_e32 v103, v100
	v_mul_f32_e32 v104, v96, v101
	v_mul_f32_e32 v105, v97, v101
	v_exp_f32_e32 v104, v104
	v_exp_f32_e32 v105, v105
	v_add_f32_e32 v102, 1.0, v102
	v_add_f32_e32 v103, 1.0, v103
	v_rcp_f32_e32 v102, v102
	v_rcp_f32_e32 v103, v103
	v_add_f32_e32 v96, 1.0, v104
	v_add_f32_e32 v97, 1.0, v105
	v_rcp_f32_e32 v96, v96
	v_rcp_f32_e32 v97, v97
	v_mul_f32_e32 v100, v169, v169
	v_pk_mul_f32 v[94:95], v[100:101], v[102:103] op_sel_hi:[0,1]
	v_pk_mul_f32 v[90:91], v[90:91], v[94:95]
	v_pk_mul_f32 v[94:95], v[100:101], v[96:97] op_sel_hi:[0,1]
	v_mul_f32_e32 v96, v86, v101
	v_mul_f32_e32 v97, v87, v101
	v_exp_f32_e32 v96, v96
	v_exp_f32_e32 v97, v97
	v_pk_mul_f32 v[92:93], v[92:93], v[94:95]
	v_mad_i64_i32 v[98:99], s[28:29], v160, s67, v[152:153]
	v_add_f32_e32 v94, 1.0, v96
	v_add_f32_e32 v95, 1.0, v97
	v_mul_f32_e32 v96, v88, v101
	v_mul_f32_e32 v97, v89, v101
	v_exp_f32_e32 v96, v96
	v_exp_f32_e32 v97, v97
	v_rcp_f32_e32 v94, v94
	v_rcp_f32_e32 v95, v95
	v_add_f32_e32 v88, 1.0, v96
	v_add_f32_e32 v89, 1.0, v97
	v_rcp_f32_e32 v88, v88
	v_rcp_f32_e32 v89, v89
	v_pk_mul_f32 v[86:87], v[100:101], v[94:95] op_sel_hi:[0,1]
	v_pk_mul_f32 v[86:87], v[82:83], v[86:87]
	v_lshl_add_u64 v[94:95], v[98:99], 0, v[114:115]
	v_pk_mul_f32 v[82:83], v[100:101], v[88:89] op_sel_hi:[0,1]
	v_pk_mul_f32 v[88:89], v[84:85], v[82:83]
	v_cvt_pk_bf16_f32 v82, v90, v91
	v_cvt_pk_bf16_f32 v83, v92, v93
	v_cvt_pk_bf16_f32 v84, v86, v87
	v_cvt_pk_bf16_f32 v85, v88, v89
	global_store_dwordx4 v[94:95], v[82:85], off
	s_nop 1
	v_mul_f32_e32 v85, 0xbfb8aa3b, v173
	v_mul_f32_e32 v84, v78, v85
	v_exp_f32_e32 v86, v84
	v_mul_f32_e32 v84, v79, v85
	v_exp_f32_e32 v87, v84
	v_mul_f32_e32 v88, v80, v85
	v_mul_f32_e32 v89, v81, v85
	v_exp_f32_e32 v88, v88
	v_exp_f32_e32 v89, v89
	v_add_f32_e32 v86, 1.0, v86
	v_add_f32_e32 v87, 1.0, v87
	v_rcp_f32_e32 v86, v86
	v_rcp_f32_e32 v87, v87
	v_add_f32_e32 v80, 1.0, v88
	v_add_f32_e32 v81, 1.0, v89
	v_rcp_f32_e32 v80, v80
	v_rcp_f32_e32 v81, v81
	v_mul_f32_e32 v84, v173, v173
	v_pk_mul_f32 v[78:79], v[84:85], v[86:87] op_sel_hi:[0,1]
	v_pk_mul_f32 v[74:75], v[74:75], v[78:79]
	v_pk_mul_f32 v[78:79], v[84:85], v[80:81] op_sel_hi:[0,1]
	v_mul_f32_e32 v80, v70, v85
	v_mul_f32_e32 v81, v71, v85
	v_exp_f32_e32 v80, v80
	v_exp_f32_e32 v81, v81
	v_pk_mul_f32 v[76:77], v[76:77], v[78:79]
	v_mad_i64_i32 v[82:83], s[28:29], v158, s67, v[152:153]
	v_add_f32_e32 v78, 1.0, v80
	v_add_f32_e32 v79, 1.0, v81
	v_mul_f32_e32 v80, v72, v85
	v_mul_f32_e32 v81, v73, v85
	v_exp_f32_e32 v80, v80
	v_exp_f32_e32 v81, v81
	v_rcp_f32_e32 v78, v78
	v_rcp_f32_e32 v79, v79
	v_add_f32_e32 v72, 1.0, v80
	v_add_f32_e32 v73, 1.0, v81
	v_rcp_f32_e32 v72, v72
	v_rcp_f32_e32 v73, v73
	v_pk_mul_f32 v[70:71], v[84:85], v[78:79] op_sel_hi:[0,1]
	v_pk_mul_f32 v[70:71], v[66:67], v[70:71]
	v_lshl_add_u64 v[78:79], v[82:83], 0, v[114:115]
	v_pk_mul_f32 v[66:67], v[84:85], v[72:73] op_sel_hi:[0,1]
	v_pk_mul_f32 v[72:73], v[68:69], v[66:67]
	v_cvt_pk_bf16_f32 v66, v74, v75
	v_cvt_pk_bf16_f32 v67, v76, v77
	v_cvt_pk_bf16_f32 v68, v70, v71
	v_cvt_pk_bf16_f32 v69, v72, v73
	global_store_dwordx4 v[78:79], v[66:69], off
	s_nop 1
	v_mul_f32_e32 v69, 0xbfb8aa3b, v176
	v_mul_f32_e32 v68, v62, v69
	v_exp_f32_e32 v70, v68
	v_mul_f32_e32 v68, v63, v69
	v_exp_f32_e32 v71, v68
	v_mul_f32_e32 v72, v64, v69
	v_mul_f32_e32 v73, v65, v69
	v_exp_f32_e32 v72, v72
	v_exp_f32_e32 v73, v73
	v_add_f32_e32 v70, 1.0, v70
	v_add_f32_e32 v71, 1.0, v71
	v_rcp_f32_e32 v70, v70
	v_rcp_f32_e32 v71, v71
	v_add_f32_e32 v64, 1.0, v72
	v_add_f32_e32 v65, 1.0, v73
	v_rcp_f32_e32 v64, v64
	v_rcp_f32_e32 v65, v65
	v_mul_f32_e32 v68, v176, v176
	v_pk_mul_f32 v[62:63], v[68:69], v[70:71] op_sel_hi:[0,1]
	v_pk_mul_f32 v[58:59], v[58:59], v[62:63]
	v_pk_mul_f32 v[62:63], v[68:69], v[64:65] op_sel_hi:[0,1]
	v_mul_f32_e32 v64, v54, v69
	v_mul_f32_e32 v65, v55, v69
	v_exp_f32_e32 v64, v64
	v_exp_f32_e32 v65, v65
	v_pk_mul_f32 v[60:61], v[60:61], v[62:63]
	v_mad_i64_i32 v[66:67], s[28:29], v156, s67, v[152:153]
	v_add_f32_e32 v62, 1.0, v64
	v_add_f32_e32 v63, 1.0, v65
	v_mul_f32_e32 v64, v56, v69
	v_mul_f32_e32 v65, v57, v69
	v_exp_f32_e32 v64, v64
	v_exp_f32_e32 v65, v65
	v_rcp_f32_e32 v62, v62
	v_rcp_f32_e32 v63, v63
	v_add_f32_e32 v56, 1.0, v64
	v_add_f32_e32 v57, 1.0, v65
	v_rcp_f32_e32 v56, v56
	v_rcp_f32_e32 v57, v57
	v_pk_mul_f32 v[54:55], v[68:69], v[62:63] op_sel_hi:[0,1]
	v_pk_mul_f32 v[54:55], v[50:51], v[54:55]
	v_lshl_add_u64 v[62:63], v[66:67], 0, v[114:115]
	v_pk_mul_f32 v[50:51], v[68:69], v[56:57] op_sel_hi:[0,1]
	v_pk_mul_f32 v[56:57], v[52:53], v[50:51]
	v_cvt_pk_bf16_f32 v50, v58, v59
	v_cvt_pk_bf16_f32 v51, v60, v61
	v_cvt_pk_bf16_f32 v52, v54, v55
	v_cvt_pk_bf16_f32 v53, v56, v57
	global_store_dwordx4 v[62:63], v[50:53], off
	s_nop 1
	v_mul_f32_e32 v53, 0xbfb8aa3b, v155
	v_mul_f32_e32 v52, v46, v53
	v_exp_f32_e32 v54, v52
	v_mul_f32_e32 v52, v47, v53
	v_exp_f32_e32 v55, v52
	v_mul_f32_e32 v56, v48, v53
	v_mul_f32_e32 v57, v49, v53
	v_exp_f32_e32 v56, v56
	v_exp_f32_e32 v57, v57
	v_add_f32_e32 v54, 1.0, v54
	v_add_f32_e32 v55, 1.0, v55
	v_rcp_f32_e32 v54, v54
	v_rcp_f32_e32 v55, v55
	v_add_f32_e32 v48, 1.0, v56
	v_add_f32_e32 v49, 1.0, v57
	v_rcp_f32_e32 v48, v48
	v_rcp_f32_e32 v49, v49
	v_mul_f32_e32 v52, v155, v155
	v_pk_mul_f32 v[46:47], v[52:53], v[54:55] op_sel_hi:[0,1]
	v_pk_mul_f32 v[42:43], v[42:43], v[46:47]
	v_pk_mul_f32 v[46:47], v[52:53], v[48:49] op_sel_hi:[0,1]
	v_mul_f32_e32 v48, v38, v53
	v_mul_f32_e32 v49, v39, v53
	v_exp_f32_e32 v48, v48
	v_exp_f32_e32 v49, v49
	v_pk_mul_f32 v[44:45], v[44:45], v[46:47]
	v_mad_i64_i32 v[50:51], s[28:29], v154, s67, v[152:153]
	v_add_f32_e32 v46, 1.0, v48
	v_add_f32_e32 v47, 1.0, v49
	v_mul_f32_e32 v48, v40, v53
	v_mul_f32_e32 v49, v41, v53
	v_exp_f32_e32 v48, v48
	v_exp_f32_e32 v49, v49
	v_rcp_f32_e32 v46, v46
	v_rcp_f32_e32 v47, v47
	v_add_f32_e32 v40, 1.0, v48
	v_add_f32_e32 v41, 1.0, v49
	v_rcp_f32_e32 v40, v40
	v_rcp_f32_e32 v41, v41
	v_pk_mul_f32 v[38:39], v[52:53], v[46:47] op_sel_hi:[0,1]
	v_pk_mul_f32 v[38:39], v[34:35], v[38:39]
	v_lshl_add_u64 v[46:47], v[50:51], 0, v[114:115]
	v_pk_mul_f32 v[34:35], v[52:53], v[40:41] op_sel_hi:[0,1]
	v_pk_mul_f32 v[40:41], v[36:37], v[34:35]
	v_cvt_pk_bf16_f32 v34, v42, v43
	v_cvt_pk_bf16_f32 v35, v44, v45
	v_cvt_pk_bf16_f32 v36, v38, v39
	v_cvt_pk_bf16_f32 v37, v40, v41
	global_store_dwordx4 v[46:47], v[34:37], off
	s_nop 1
	v_mul_f32_e32 v37, 0xbfb8aa3b, v151
	v_mul_f32_e32 v36, v30, v37
	v_exp_f32_e32 v38, v36
	v_mul_f32_e32 v36, v31, v37
	v_exp_f32_e32 v39, v36
	v_mul_f32_e32 v40, v32, v37
	v_mul_f32_e32 v41, v33, v37
	v_exp_f32_e32 v40, v40
	v_exp_f32_e32 v41, v41
	v_add_f32_e32 v38, 1.0, v38
	v_add_f32_e32 v39, 1.0, v39
	v_rcp_f32_e32 v38, v38
	v_rcp_f32_e32 v39, v39
	v_add_f32_e32 v32, 1.0, v40
	v_add_f32_e32 v33, 1.0, v41
	v_rcp_f32_e32 v32, v32
	v_rcp_f32_e32 v33, v33
	v_mul_f32_e32 v36, v151, v151
	v_pk_mul_f32 v[30:31], v[36:37], v[38:39] op_sel_hi:[0,1]
	v_pk_mul_f32 v[26:27], v[26:27], v[30:31]
	v_pk_mul_f32 v[30:31], v[36:37], v[32:33] op_sel_hi:[0,1]
	v_mul_f32_e32 v32, v22, v37
	v_mul_f32_e32 v33, v23, v37
	v_exp_f32_e32 v32, v32
	v_exp_f32_e32 v33, v33
	v_pk_mul_f32 v[28:29], v[28:29], v[30:31]
	v_mad_i64_i32 v[34:35], s[28:29], v150, s67, v[152:153]
	v_add_f32_e32 v30, 1.0, v32
	v_add_f32_e32 v31, 1.0, v33
	v_mul_f32_e32 v32, v24, v37
	v_mul_f32_e32 v33, v25, v37
	v_exp_f32_e32 v32, v32
	v_exp_f32_e32 v33, v33
	v_rcp_f32_e32 v30, v30
	v_rcp_f32_e32 v31, v31
	v_add_f32_e32 v24, 1.0, v32
	v_add_f32_e32 v25, 1.0, v33
	v_rcp_f32_e32 v24, v24
	v_rcp_f32_e32 v25, v25
	v_pk_mul_f32 v[22:23], v[36:37], v[30:31] op_sel_hi:[0,1]
	v_pk_mul_f32 v[22:23], v[18:19], v[22:23]
	v_lshl_add_u64 v[30:31], v[34:35], 0, v[114:115]
	v_pk_mul_f32 v[18:19], v[36:37], v[24:25] op_sel_hi:[0,1]
	v_pk_mul_f32 v[24:25], v[20:21], v[18:19]
	v_cvt_pk_bf16_f32 v18, v26, v27
	v_cvt_pk_bf16_f32 v19, v28, v29
	v_cvt_pk_bf16_f32 v20, v22, v23
	v_cvt_pk_bf16_f32 v21, v24, v25
	global_store_dwordx4 v[30:31], v[18:21], off
	s_nop 1
	v_mul_f32_e32 v21, 0xbfb8aa3b, v149
	v_mul_f32_e32 v20, v14, v21
	v_exp_f32_e32 v22, v20
	v_mul_f32_e32 v20, v15, v21
	v_exp_f32_e32 v23, v20
	v_mul_f32_e32 v24, v16, v21
	v_mul_f32_e32 v25, v17, v21
	v_exp_f32_e32 v24, v24
	v_exp_f32_e32 v25, v25
	v_add_f32_e32 v22, 1.0, v22
	v_add_f32_e32 v23, 1.0, v23
	v_rcp_f32_e32 v22, v22
	v_rcp_f32_e32 v23, v23
	v_add_f32_e32 v16, 1.0, v24
	v_add_f32_e32 v17, 1.0, v25
	v_rcp_f32_e32 v16, v16
	v_rcp_f32_e32 v17, v17
	v_mul_f32_e32 v20, v149, v149
	v_pk_mul_f32 v[14:15], v[20:21], v[22:23] op_sel_hi:[0,1]
	v_pk_mul_f32 v[10:11], v[10:11], v[14:15]
	v_pk_mul_f32 v[14:15], v[20:21], v[16:17] op_sel_hi:[0,1]
	v_mul_f32_e32 v16, v6, v21
	v_mul_f32_e32 v17, v7, v21
	v_exp_f32_e32 v16, v16
	v_exp_f32_e32 v17, v17
	v_pk_mul_f32 v[12:13], v[12:13], v[14:15]
	v_mad_i64_i32 v[18:19], s[28:29], v148, s67, v[152:153]
	v_add_f32_e32 v14, 1.0, v16
	v_add_f32_e32 v15, 1.0, v17
	v_mul_f32_e32 v16, v8, v21
	v_mul_f32_e32 v17, v9, v21
	v_exp_f32_e32 v16, v16
	v_exp_f32_e32 v17, v17
	v_rcp_f32_e32 v14, v14
	v_rcp_f32_e32 v15, v15
	v_add_f32_e32 v8, 1.0, v16
	v_add_f32_e32 v9, 1.0, v17
	v_rcp_f32_e32 v8, v8
	v_rcp_f32_e32 v9, v9
	v_pk_mul_f32 v[6:7], v[20:21], v[14:15] op_sel_hi:[0,1]
	v_pk_mul_f32 v[6:7], v[2:3], v[6:7]
	v_lshl_add_u64 v[14:15], v[18:19], 0, v[114:115]
	v_pk_mul_f32 v[2:3], v[20:21], v[8:9] op_sel_hi:[0,1]
	v_pk_mul_f32 v[8:9], v[4:5], v[2:3]
	v_cvt_pk_bf16_f32 v2, v10, v11
	v_cvt_pk_bf16_f32 v3, v12, v13
	v_cvt_pk_bf16_f32 v4, v6, v7
	v_cvt_pk_bf16_f32 v5, v8, v9
	global_store_dwordx4 v[14:15], v[2:5], off
	s_cbranch_vccnz .LBB0_166
	s_andn2_b64 vcc, exec, s[0:1]
	s_cbranch_vccnz .LBB0_165
	s_barrier
	s_branch .LBB0_165

.LBB0_1904:
	s_ashr_i32 s51, s50, 31
	s_lshl_b64 s[52:53], s[50:51], 19
	s_add_u32 s52, s80, s52
	s_addc_u32 s53, s81, s53
	s_and_b64 s[54:55], s[4:5], exec
	s_cselect_b32 s51, s53, s31
	s_cselect_b32 s60, s52, s30
	s_ashr_i32 s49, s48, 31
	s_lshl_b64 s[54:55], s[48:49], 19
	s_add_u32 s54, s24, s54
	s_addc_u32 s55, s25, s55
	s_and_b64 s[58:59], s[4:5], exec
	s_cselect_b32 s49, s55, s29
	s_cselect_b32 s61, s54, s28
	s_cmp_ge_u32 s33, 0x1000
	s_cbranch_scc1 .Lst8_skip
	s_lshl_b32 s58, s56, 12
	s_add_u32 s58, s20, s58
	s_addc_u32 s59, s21, 0
	s_and_b32 s72, s71, 1
	s_lshl_b32 s72, s72, 12
	s_add_i32 s72, s72, 0x20000
	s_add_i32 m0, s33, s72
	v_lshlrev_b32_e32 v202, 4, v0
	s_nop 0
	global_load_lds_dwordx4 v202, s[58:59]
.Lst8_skip:
	s_add_u32 s58, s30, 0x40080
	s_addc_u32 s59, s31, 0
	s_add_u32 s72, s28, 0x100
	v_mov_b32_e32 v2, 0
	v_mov_b32_e32 v3, 0
	v_mov_b64_e32 v[4:5], v[2:3]
	v_mov_b64_e32 v[6:7], v[2:3]
	v_mov_b64_e32 v[8:9], v[2:3]
	v_mov_b64_e32 v[10:11], v[2:3]
	v_mov_b64_e32 v[12:13], v[2:3]
	v_mov_b64_e32 v[14:15], v[2:3]
	v_mov_b64_e32 v[16:17], v[2:3]
	v_mov_b64_e32 v[18:19], v[2:3]
	v_mov_b64_e32 v[20:21], v[2:3]
	v_mov_b64_e32 v[22:23], v[2:3]
	v_mov_b64_e32 v[24:25], v[2:3]
	v_mov_b64_e32 v[26:27], v[2:3]
	v_mov_b64_e32 v[28:29], v[2:3]
	v_mov_b64_e32 v[30:31], v[2:3]
	v_mov_b64_e32 v[32:33], v[2:3]
	v_mov_b64_e32 v[34:35], v[2:3]
	v_mov_b64_e32 v[36:37], v[2:3]
	v_mov_b64_e32 v[38:39], v[2:3]
	v_mov_b64_e32 v[40:41], v[2:3]
	v_mov_b64_e32 v[42:43], v[2:3]
	v_mov_b64_e32 v[44:45], v[2:3]
	v_mov_b64_e32 v[46:47], v[2:3]
	v_mov_b64_e32 v[48:49], v[2:3]
	v_mov_b64_e32 v[50:51], v[2:3]
	v_mov_b64_e32 v[52:53], v[2:3]
	v_mov_b64_e32 v[54:55], v[2:3]
	v_mov_b64_e32 v[56:57], v[2:3]
	v_mov_b64_e32 v[58:59], v[2:3]
	v_mov_b64_e32 v[60:61], v[2:3]
	v_mov_b64_e32 v[62:63], v[2:3]
	v_mov_b64_e32 v[64:65], v[2:3]
	v_mov_b64_e32 v[66:67], v[2:3]
	v_mov_b64_e32 v[68:69], v[2:3]
	v_mov_b64_e32 v[70:71], v[2:3]
	v_mov_b64_e32 v[72:73], v[2:3]
	v_mov_b64_e32 v[74:75], v[2:3]
	v_mov_b64_e32 v[76:77], v[2:3]
	v_mov_b64_e32 v[78:79], v[2:3]
	v_mov_b64_e32 v[80:81], v[2:3]
	v_mov_b64_e32 v[82:83], v[2:3]
	v_mov_b64_e32 v[84:85], v[2:3]
	v_mov_b64_e32 v[86:87], v[2:3]
	v_mov_b64_e32 v[88:89], v[2:3]
	v_mov_b64_e32 v[90:91], v[2:3]
	v_mov_b64_e32 v[92:93], v[2:3]
	v_mov_b64_e32 v[94:95], v[2:3]
	v_mov_b64_e32 v[96:97], v[2:3]
	v_mov_b64_e32 v[98:99], v[2:3]
	v_mov_b64_e32 v[100:101], v[2:3]
	v_mov_b64_e32 v[102:103], v[2:3]
	v_mov_b64_e32 v[104:105], v[2:3]
	v_mov_b64_e32 v[106:107], v[2:3]
	v_mov_b64_e32 v[108:109], v[2:3]
	v_mov_b64_e32 v[110:111], v[2:3]
	v_mov_b64_e32 v[112:113], v[2:3]
	v_mov_b64_e32 v[114:115], v[2:3]
	v_mov_b64_e32 v[116:117], v[2:3]
	v_mov_b64_e32 v[118:119], v[2:3]
	v_mov_b64_e32 v[120:121], v[2:3]
	v_mov_b64_e32 v[122:123], v[2:3]
	v_mov_b64_e32 v[124:125], v[2:3]
	v_mov_b64_e32 v[126:127], v[2:3]
	v_mov_b64_e32 v[128:129], v[2:3]
	s_addc_u32 s73, s29, 0
	s_mov_b32 s74, -2
	s_waitcnt vmcnt(0)

.LBB0_1923:
	v_lshl_add_u32 v202, s56, 8, v1
	s_and_b32 s72, s71, 1
	s_lshl_b32 s72, s72, 12
	s_add_i32 s72, s72, 0x20000
	v_lshl_add_u32 v206, v1, 4, s72
	v_or_b32_e32 v162, 16, v202
	v_ashrrev_i32_e32 v203, 31, v202
	v_ashrrev_i32_e32 v163, 31, v162
	v_or_b32_e32 v160, 32, v202
	v_or_b32_e32 v158, 48, v202
	v_ashrrev_i32_e32 v161, 31, v160
	v_ashrrev_i32_e32 v159, 31, v158
	v_add_u32_e32 v156, 0x80, v202
	v_add_u32_e32 v154, 0x90, v202
	ds_read_b128 v[170:173], v206
	ds_read_b128 v[174:177], v206 offset:256
	v_ashrrev_i32_e32 v157, 31, v156
	v_ashrrev_i32_e32 v155, 31, v154
	ds_read_b128 v[178:181], v206 offset:512
	ds_read_b128 v[182:185], v206 offset:768
	ds_read_b128 v[186:189], v206 offset:2048
	ds_read_b128 v[190:193], v206 offset:2304
	v_add_u32_e32 v150, 0xa0, v202
	v_ashrrev_i32_e32 v151, 31, v150
	ds_read_b128 v[194:197], v206 offset:2560
	v_add_u32_e32 v148, 0xb0, v202
	v_ashrrev_i32_e32 v149, 31, v148
	ds_read_b128 v[198:201], v206 offset:2816
	v_pk_mul_f32 v[124:125], v[128:129], v[124:125]
	v_pk_mul_f32 v[122:123], v[126:127], v[122:123]
	v_pk_mul_f32 v[116:117], v[120:121], v[116:117]
	v_lshl_or_b32 v204, s14, 7, v164
	v_pk_mul_f32 v[114:115], v[118:119], v[114:115]
	v_ashrrev_i32_e32 v205, 31, v204
	v_pk_mul_f32 v[108:109], v[112:113], v[108:109]
	v_pk_mul_f32 v[106:107], v[110:111], v[106:107]
	v_pk_mul_f32 v[100:101], v[104:105], v[100:101]
	v_pk_mul_f32 v[98:99], v[102:103], v[98:99]
	v_pk_mul_f32 v[92:93], v[96:97], v[92:93]
	v_pk_mul_f32 v[90:91], v[94:95], v[90:91]
	v_pk_mul_f32 v[84:85], v[88:89], v[84:85]
	v_pk_mul_f32 v[82:83], v[86:87], v[82:83]
	v_pk_mul_f32 v[76:77], v[80:81], v[76:77]
	v_pk_mul_f32 v[74:75], v[78:79], v[74:75]
	v_pk_mul_f32 v[68:69], v[72:73], v[68:69]
	v_pk_mul_f32 v[66:67], v[70:71], v[66:67]
	v_pk_mul_f32 v[60:61], v[64:65], v[60:61]
	v_pk_mul_f32 v[58:59], v[62:63], v[58:59]
	v_pk_mul_f32 v[52:53], v[56:57], v[52:53]
	v_pk_mul_f32 v[50:51], v[54:55], v[50:51]
	v_pk_mul_f32 v[44:45], v[48:49], v[44:45]
	v_pk_mul_f32 v[42:43], v[46:47], v[42:43]
	v_pk_mul_f32 v[36:37], v[40:41], v[36:37]
	v_pk_mul_f32 v[34:35], v[38:39], v[34:35]
	v_pk_mul_f32 v[28:29], v[32:33], v[28:29]
	v_pk_mul_f32 v[26:27], v[30:31], v[26:27]
	v_pk_mul_f32 v[20:21], v[24:25], v[20:21]
	v_pk_mul_f32 v[18:19], v[22:23], v[18:19]
	v_pk_mul_f32 v[12:13], v[16:17], v[12:13]
	v_pk_mul_f32 v[10:11], v[14:15], v[10:11]
	v_pk_mul_f32 v[4:5], v[8:9], v[4:5]
	v_pk_mul_f32 v[2:3], v[6:7], v[2:3]
	s_andn2_b64 vcc, exec, s[46:47]
	s_waitcnt lgkmcnt(0)
	v_mov_b32_e32 v152, v171
	v_mov_b32_e32 v153, v172
	v_mov_b32_e32 v171, v173
	v_pk_add_f32 v[152:153], v[152:153], v[170:171]
	v_mov_b32_e32 v170, v175
	v_add_f32_e32 v149, v152, v153
	v_fmamk_f32 v149, v149, 0x3a800000, v168
	v_mov_b32_e32 v171, v176
	v_mov_b32_e32 v175, v177
	v_mov_b32_e32 v172, v179
	v_mov_b32_e32 v173, v180
	v_mov_b32_e32 v179, v181
	v_mov_b32_e32 v176, v183
	v_mov_b32_e32 v177, v184
	v_mov_b32_e32 v183, v185
	v_mov_b32_e32 v180, v187
	v_mov_b32_e32 v181, v188
	v_mov_b32_e32 v187, v189
	v_mov_b32_e32 v184, v191
	v_mov_b32_e32 v185, v192
	v_mov_b32_e32 v191, v193
	v_mov_b32_e32 v188, v195
	v_mov_b32_e32 v189, v196
	v_mov_b32_e32 v195, v197
	v_rsq_f32_e32 v163, v149
	v_mov_b32_e32 v192, v199
	v_mov_b32_e32 v193, v200
	v_mov_b32_e32 v199, v201
	v_pk_add_f32 v[152:153], v[170:171], v[174:175]
	v_pk_add_f32 v[170:171], v[172:173], v[178:179]
	v_pk_add_f32 v[172:173], v[176:177], v[182:183]
	v_pk_add_f32 v[174:175], v[180:181], v[186:187]
	v_pk_add_f32 v[176:177], v[184:185], v[190:191]
	v_pk_add_f32 v[178:179], v[188:189], v[194:195]
	v_pk_add_f32 v[180:181], v[192:193], v[198:199]
	v_add_f32_e32 v151, v152, v153
	v_add_f32_e32 v152, v170, v171
	v_add_f32_e32 v153, v172, v173
	v_add_f32_e32 v155, v174, v175
	v_add_f32_e32 v157, v176, v177
	v_add_f32_e32 v159, v178, v179
	v_add_f32_e32 v161, v180, v181
	v_fmamk_f32 v149, v151, 0x3a800000, v168
	v_fmamk_f32 v151, v152, 0x3a800000, v168
	v_fmamk_f32 v152, v153, 0x3a800000, v168
	v_fmamk_f32 v153, v155, 0x3a800000, v168
	v_fmamk_f32 v155, v157, 0x3a800000, v168
	v_fmamk_f32 v157, v159, 0x3a800000, v168
	v_fmamk_f32 v159, v161, 0x3a800000, v168
	v_rsq_f32_e32 v169, v151
	v_rsq_f32_e32 v151, v157
	v_mul_f32_e32 v157, 0xbfb8aa3b, v163
	v_rsq_f32_e32 v161, v149
	v_rsq_f32_e32 v149, v159
	v_mul_f32_e32 v159, v126, v157
	v_exp_f32_e32 v159, v159
	v_mul_f32_e32 v172, v127, v157
	v_exp_f32_e32 v175, v172
	v_mul_f32_e32 v172, v163, v163
	v_add_f32_e32 v159, 1.0, v159
	v_rcp_f32_e32 v174, v159
	v_add_f32_e32 v159, 1.0, v175
	v_rcp_f32_e32 v175, v159
	v_mul_f32_e32 v159, v128, v157
	v_mul_f32_e32 v163, v129, v157
	v_exp_f32_e32 v159, v159
	v_exp_f32_e32 v163, v163
	v_rsq_f32_e32 v173, v152
	v_rsq_f32_e32 v176, v153
	v_add_f32_e32 v128, 1.0, v159
	v_add_f32_e32 v129, 1.0, v163
	v_rcp_f32_e32 v128, v128
	v_rcp_f32_e32 v129, v129
	v_pk_mul_f32 v[126:127], v[172:173], v[174:175] op_sel_hi:[0,1]
	v_pk_mul_f32 v[122:123], v[122:123], v[126:127]
	v_mov_b64_e32 v[152:153], s[18:19]
	v_pk_mul_f32 v[126:127], v[172:173], v[128:129] op_sel_hi:[0,1]
	v_mul_f32_e32 v128, v118, v157
	v_mul_f32_e32 v129, v119, v157
	v_exp_f32_e32 v128, v128
	v_exp_f32_e32 v129, v129
	v_pk_mul_f32 v[124:125], v[124:125], v[126:127]
	v_mad_i64_i32 v[170:171], s[28:29], v202, s70, v[152:153]
	v_add_f32_e32 v126, 1.0, v128
	v_add_f32_e32 v127, 1.0, v129
	v_mul_f32_e32 v128, v120, v157
	v_mul_f32_e32 v129, v121, v157
	v_exp_f32_e32 v128, v128
	v_exp_f32_e32 v129, v129
	v_rcp_f32_e32 v126, v126
	v_rcp_f32_e32 v127, v127
	v_add_f32_e32 v120, 1.0, v128
	v_add_f32_e32 v121, 1.0, v129
	v_rcp_f32_e32 v120, v120
	v_rcp_f32_e32 v121, v121
	v_pk_mul_f32 v[118:119], v[172:173], v[126:127] op_sel_hi:[0,1]
	v_pk_mul_f32 v[118:119], v[114:115], v[118:119]
	v_rsq_f32_e32 v155, v155
	v_pk_mul_f32 v[114:115], v[172:173], v[120:121] op_sel_hi:[0,1]
	v_pk_mul_f32 v[120:121], v[116:117], v[114:115]
	v_lshlrev_b64 v[114:115], 1, v[204:205]
	v_lshl_add_u64 v[126:127], v[170:171], 0, v[114:115]
	v_cvt_pk_bf16_f32 v116, v122, v123
	v_cvt_pk_bf16_f32 v117, v124, v125
	v_cvt_pk_bf16_f32 v118, v118, v119
	v_cvt_pk_bf16_f32 v119, v120, v121
	global_store_dwordx4 v[126:127], v[116:119], off
	s_nop 1
	v_mul_f32_e32 v119, 0xbfb8aa3b, v161
	v_mul_f32_e32 v118, v110, v119
	v_exp_f32_e32 v120, v118
	v_mul_f32_e32 v118, v111, v119
	v_exp_f32_e32 v121, v118
	v_mul_f32_e32 v122, v112, v119
	v_mul_f32_e32 v123, v113, v119
	v_exp_f32_e32 v122, v122
	v_exp_f32_e32 v123, v123
	v_add_f32_e32 v120, 1.0, v120
	v_add_f32_e32 v121, 1.0, v121
	v_rcp_f32_e32 v120, v120
	v_rcp_f32_e32 v121, v121
	v_add_f32_e32 v112, 1.0, v122
	v_add_f32_e32 v113, 1.0, v123
	v_rcp_f32_e32 v112, v112
	v_rcp_f32_e32 v113, v113
	v_mul_f32_e32 v118, v161, v161
	v_pk_mul_f32 v[110:111], v[118:119], v[120:121] op_sel_hi:[0,1]
	v_pk_mul_f32 v[106:107], v[106:107], v[110:111]
	v_pk_mul_f32 v[110:111], v[118:119], v[112:113] op_sel_hi:[0,1]
	v_mul_f32_e32 v112, v102, v119
	v_mul_f32_e32 v113, v103, v119
	v_exp_f32_e32 v112, v112
	v_exp_f32_e32 v113, v113
	v_pk_mul_f32 v[108:109], v[108:109], v[110:111]
	v_mad_i64_i32 v[116:117], s[28:29], v162, s70, v[152:153]
	v_add_f32_e32 v110, 1.0, v112
	v_add_f32_e32 v111, 1.0, v113
	v_mul_f32_e32 v112, v104, v119
	v_mul_f32_e32 v113, v105, v119
	v_exp_f32_e32 v112, v112
	v_exp_f32_e32 v113, v113
	v_rcp_f32_e32 v110, v110
	v_rcp_f32_e32 v111, v111
	v_add_f32_e32 v104, 1.0, v112
	v_add_f32_e32 v105, 1.0, v113
	v_rcp_f32_e32 v104, v104
	v_rcp_f32_e32 v105, v105
	v_pk_mul_f32 v[102:103], v[118:119], v[110:111] op_sel_hi:[0,1]
	v_pk_mul_f32 v[102:103], v[98:99], v[102:103]
	v_lshl_add_u64 v[110:111], v[116:117], 0, v[114:115]
	v_pk_mul_f32 v[98:99], v[118:119], v[104:105] op_sel_hi:[0,1]
	v_pk_mul_f32 v[104:105], v[100:101], v[98:99]
	v_cvt_pk_bf16_f32 v98, v106, v107
	v_cvt_pk_bf16_f32 v99, v108, v109
	v_cvt_pk_bf16_f32 v100, v102, v103
	v_cvt_pk_bf16_f32 v101, v104, v105
	global_store_dwordx4 v[110:111], v[98:101], off
	s_nop 1
	v_mul_f32_e32 v101, 0xbfb8aa3b, v169
	v_mul_f32_e32 v100, v94, v101
	v_exp_f32_e32 v102, v100
	v_mul_f32_e32 v100, v95, v101
	v_exp_f32_e32 v103, v100
	v_mul_f32_e32 v104, v96, v101
	v_mul_f32_e32 v105, v97, v101
	v_exp_f32_e32 v104, v104
	v_exp_f32_e32 v105, v105
	v_add_f32_e32 v102, 1.0, v102
	v_add_f32_e32 v103, 1.0, v103
	v_rcp_f32_e32 v102, v102
	v_rcp_f32_e32 v103, v103
	v_add_f32_e32 v96, 1.0, v104
	v_add_f32_e32 v97, 1.0, v105
	v_rcp_f32_e32 v96, v96
	v_rcp_f32_e32 v97, v97
	v_mul_f32_e32 v100, v169, v169
	v_pk_mul_f32 v[94:95], v[100:101], v[102:103] op_sel_hi:[0,1]
	v_pk_mul_f32 v[90:91], v[90:91], v[94:95]
	v_pk_mul_f32 v[94:95], v[100:101], v[96:97] op_sel_hi:[0,1]
	v_mul_f32_e32 v96, v86, v101
	v_mul_f32_e32 v97, v87, v101
	v_exp_f32_e32 v96, v96
	v_exp_f32_e32 v97, v97
	v_pk_mul_f32 v[92:93], v[92:93], v[94:95]
	v_mad_i64_i32 v[98:99], s[28:29], v160, s70, v[152:153]
	v_add_f32_e32 v94, 1.0, v96
	v_add_f32_e32 v95, 1.0, v97
	v_mul_f32_e32 v96, v88, v101
	v_mul_f32_e32 v97, v89, v101
	v_exp_f32_e32 v96, v96
	v_exp_f32_e32 v97, v97
	v_rcp_f32_e32 v94, v94
	v_rcp_f32_e32 v95, v95
	v_add_f32_e32 v88, 1.0, v96
	v_add_f32_e32 v89, 1.0, v97
	v_rcp_f32_e32 v88, v88
	v_rcp_f32_e32 v89, v89
	v_pk_mul_f32 v[86:87], v[100:101], v[94:95] op_sel_hi:[0,1]
	v_pk_mul_f32 v[86:87], v[82:83], v[86:87]
	v_lshl_add_u64 v[94:95], v[98:99], 0, v[114:115]
	v_pk_mul_f32 v[82:83], v[100:101], v[88:89] op_sel_hi:[0,1]
	v_pk_mul_f32 v[88:89], v[84:85], v[82:83]
	v_cvt_pk_bf16_f32 v82, v90, v91
	v_cvt_pk_bf16_f32 v83, v92, v93
	v_cvt_pk_bf16_f32 v84, v86, v87
	v_cvt_pk_bf16_f32 v85, v88, v89
	global_store_dwordx4 v[94:95], v[82:85], off
	s_nop 1
	v_mul_f32_e32 v85, 0xbfb8aa3b, v173
	v_mul_f32_e32 v84, v78, v85
	v_exp_f32_e32 v86, v84
	v_mul_f32_e32 v84, v79, v85
	v_exp_f32_e32 v87, v84
	v_mul_f32_e32 v88, v80, v85
	v_mul_f32_e32 v89, v81, v85
	v_exp_f32_e32 v88, v88
	v_exp_f32_e32 v89, v89
	v_add_f32_e32 v86, 1.0, v86
	v_add_f32_e32 v87, 1.0, v87
	v_rcp_f32_e32 v86, v86
	v_rcp_f32_e32 v87, v87
	v_add_f32_e32 v80, 1.0, v88
	v_add_f32_e32 v81, 1.0, v89
	v_rcp_f32_e32 v80, v80
	v_rcp_f32_e32 v81, v81
	v_mul_f32_e32 v84, v173, v173
	v_pk_mul_f32 v[78:79], v[84:85], v[86:87] op_sel_hi:[0,1]
	v_pk_mul_f32 v[74:75], v[74:75], v[78:79]
	v_pk_mul_f32 v[78:79], v[84:85], v[80:81] op_sel_hi:[0,1]
	v_mul_f32_e32 v80, v70, v85
	v_mul_f32_e32 v81, v71, v85
	v_exp_f32_e32 v80, v80
	v_exp_f32_e32 v81, v81
	v_pk_mul_f32 v[76:77], v[76:77], v[78:79]
	v_mad_i64_i32 v[82:83], s[28:29], v158, s70, v[152:153]
	v_add_f32_e32 v78, 1.0, v80
	v_add_f32_e32 v79, 1.0, v81
	v_mul_f32_e32 v80, v72, v85
	v_mul_f32_e32 v81, v73, v85
	v_exp_f32_e32 v80, v80
	v_exp_f32_e32 v81, v81
	v_rcp_f32_e32 v78, v78
	v_rcp_f32_e32 v79, v79
	v_add_f32_e32 v72, 1.0, v80
	v_add_f32_e32 v73, 1.0, v81
	v_rcp_f32_e32 v72, v72
	v_rcp_f32_e32 v73, v73
	v_pk_mul_f32 v[70:71], v[84:85], v[78:79] op_sel_hi:[0,1]
	v_pk_mul_f32 v[70:71], v[66:67], v[70:71]
	v_lshl_add_u64 v[78:79], v[82:83], 0, v[114:115]
	v_pk_mul_f32 v[66:67], v[84:85], v[72:73] op_sel_hi:[0,1]
	v_pk_mul_f32 v[72:73], v[68:69], v[66:67]
	v_cvt_pk_bf16_f32 v66, v74, v75
	v_cvt_pk_bf16_f32 v67, v76, v77
	v_cvt_pk_bf16_f32 v68, v70, v71
	v_cvt_pk_bf16_f32 v69, v72, v73
	global_store_dwordx4 v[78:79], v[66:69], off
	s_nop 1
	v_mul_f32_e32 v69, 0xbfb8aa3b, v176
	v_mul_f32_e32 v68, v62, v69
	v_exp_f32_e32 v70, v68
	v_mul_f32_e32 v68, v63, v69
	v_exp_f32_e32 v71, v68
	v_mul_f32_e32 v72, v64, v69
	v_mul_f32_e32 v73, v65, v69
	v_exp_f32_e32 v72, v72
	v_exp_f32_e32 v73, v73
	v_add_f32_e32 v70, 1.0, v70
	v_add_f32_e32 v71, 1.0, v71
	v_rcp_f32_e32 v70, v70
	v_rcp_f32_e32 v71, v71
	v_add_f32_e32 v64, 1.0, v72
	v_add_f32_e32 v65, 1.0, v73
	v_rcp_f32_e32 v64, v64
	v_rcp_f32_e32 v65, v65
	v_mul_f32_e32 v68, v176, v176
	v_pk_mul_f32 v[62:63], v[68:69], v[70:71] op_sel_hi:[0,1]
	v_pk_mul_f32 v[58:59], v[58:59], v[62:63]
	v_pk_mul_f32 v[62:63], v[68:69], v[64:65] op_sel_hi:[0,1]
	v_mul_f32_e32 v64, v54, v69
	v_mul_f32_e32 v65, v55, v69
	v_exp_f32_e32 v64, v64
	v_exp_f32_e32 v65, v65
	v_pk_mul_f32 v[60:61], v[60:61], v[62:63]
	v_mad_i64_i32 v[66:67], s[28:29], v156, s70, v[152:153]
	v_add_f32_e32 v62, 1.0, v64
	v_add_f32_e32 v63, 1.0, v65
	v_mul_f32_e32 v64, v56, v69
	v_mul_f32_e32 v65, v57, v69
	v_exp_f32_e32 v64, v64
	v_exp_f32_e32 v65, v65
	v_rcp_f32_e32 v62, v62
	v_rcp_f32_e32 v63, v63
	v_add_f32_e32 v56, 1.0, v64
	v_add_f32_e32 v57, 1.0, v65
	v_rcp_f32_e32 v56, v56
	v_rcp_f32_e32 v57, v57
	v_pk_mul_f32 v[54:55], v[68:69], v[62:63] op_sel_hi:[0,1]
	v_pk_mul_f32 v[54:55], v[50:51], v[54:55]
	v_lshl_add_u64 v[62:63], v[66:67], 0, v[114:115]
	v_pk_mul_f32 v[50:51], v[68:69], v[56:57] op_sel_hi:[0,1]
	v_pk_mul_f32 v[56:57], v[52:53], v[50:51]
	v_cvt_pk_bf16_f32 v50, v58, v59
	v_cvt_pk_bf16_f32 v51, v60, v61
	v_cvt_pk_bf16_f32 v52, v54, v55
	v_cvt_pk_bf16_f32 v53, v56, v57
	global_store_dwordx4 v[62:63], v[50:53], off
	s_nop 1
	v_mul_f32_e32 v53, 0xbfb8aa3b, v155
	v_mul_f32_e32 v52, v46, v53
	v_exp_f32_e32 v54, v52
	v_mul_f32_e32 v52, v47, v53
	v_exp_f32_e32 v55, v52
	v_mul_f32_e32 v56, v48, v53
	v_mul_f32_e32 v57, v49, v53
	v_exp_f32_e32 v56, v56
	v_exp_f32_e32 v57, v57
	v_add_f32_e32 v54, 1.0, v54
	v_add_f32_e32 v55, 1.0, v55
	v_rcp_f32_e32 v54, v54
	v_rcp_f32_e32 v55, v55
	v_add_f32_e32 v48, 1.0, v56
	v_add_f32_e32 v49, 1.0, v57
	v_rcp_f32_e32 v48, v48
	v_rcp_f32_e32 v49, v49
	v_mul_f32_e32 v52, v155, v155
	v_pk_mul_f32 v[46:47], v[52:53], v[54:55] op_sel_hi:[0,1]
	v_pk_mul_f32 v[42:43], v[42:43], v[46:47]
	v_pk_mul_f32 v[46:47], v[52:53], v[48:49] op_sel_hi:[0,1]
	v_mul_f32_e32 v48, v38, v53
	v_mul_f32_e32 v49, v39, v53
	v_exp_f32_e32 v48, v48
	v_exp_f32_e32 v49, v49
	v_pk_mul_f32 v[44:45], v[44:45], v[46:47]
	v_mad_i64_i32 v[50:51], s[28:29], v154, s70, v[152:153]
	v_add_f32_e32 v46, 1.0, v48
	v_add_f32_e32 v47, 1.0, v49
	v_mul_f32_e32 v48, v40, v53
	v_mul_f32_e32 v49, v41, v53
	v_exp_f32_e32 v48, v48
	v_exp_f32_e32 v49, v49
	v_rcp_f32_e32 v46, v46
	v_rcp_f32_e32 v47, v47
	v_add_f32_e32 v40, 1.0, v48
	v_add_f32_e32 v41, 1.0, v49
	v_rcp_f32_e32 v40, v40
	v_rcp_f32_e32 v41, v41
	v_pk_mul_f32 v[38:39], v[52:53], v[46:47] op_sel_hi:[0,1]
	v_pk_mul_f32 v[38:39], v[34:35], v[38:39]
	v_lshl_add_u64 v[46:47], v[50:51], 0, v[114:115]
	v_pk_mul_f32 v[34:35], v[52:53], v[40:41] op_sel_hi:[0,1]
	v_pk_mul_f32 v[40:41], v[36:37], v[34:35]
	v_cvt_pk_bf16_f32 v34, v42, v43
	v_cvt_pk_bf16_f32 v35, v44, v45
	v_cvt_pk_bf16_f32 v36, v38, v39
	v_cvt_pk_bf16_f32 v37, v40, v41
	global_store_dwordx4 v[46:47], v[34:37], off
	s_nop 1
	v_mul_f32_e32 v37, 0xbfb8aa3b, v151
	v_mul_f32_e32 v36, v30, v37
	v_exp_f32_e32 v38, v36
	v_mul_f32_e32 v36, v31, v37
	v_exp_f32_e32 v39, v36
	v_mul_f32_e32 v40, v32, v37
	v_mul_f32_e32 v41, v33, v37
	v_exp_f32_e32 v40, v40
	v_exp_f32_e32 v41, v41
	v_add_f32_e32 v38, 1.0, v38
	v_add_f32_e32 v39, 1.0, v39
	v_rcp_f32_e32 v38, v38
	v_rcp_f32_e32 v39, v39
	v_add_f32_e32 v32, 1.0, v40
	v_add_f32_e32 v33, 1.0, v41
	v_rcp_f32_e32 v32, v32
	v_rcp_f32_e32 v33, v33
	v_mul_f32_e32 v36, v151, v151
	v_pk_mul_f32 v[30:31], v[36:37], v[38:39] op_sel_hi:[0,1]
	v_pk_mul_f32 v[26:27], v[26:27], v[30:31]
	v_pk_mul_f32 v[30:31], v[36:37], v[32:33] op_sel_hi:[0,1]
	v_mul_f32_e32 v32, v22, v37
	v_mul_f32_e32 v33, v23, v37
	v_exp_f32_e32 v32, v32
	v_exp_f32_e32 v33, v33
	v_pk_mul_f32 v[28:29], v[28:29], v[30:31]
	v_mad_i64_i32 v[34:35], s[28:29], v150, s70, v[152:153]
	v_add_f32_e32 v30, 1.0, v32
	v_add_f32_e32 v31, 1.0, v33
	v_mul_f32_e32 v32, v24, v37
	v_mul_f32_e32 v33, v25, v37
	v_exp_f32_e32 v32, v32
	v_exp_f32_e32 v33, v33
	v_rcp_f32_e32 v30, v30
	v_rcp_f32_e32 v31, v31
	v_add_f32_e32 v24, 1.0, v32
	v_add_f32_e32 v25, 1.0, v33
	v_rcp_f32_e32 v24, v24
	v_rcp_f32_e32 v25, v25
	v_pk_mul_f32 v[22:23], v[36:37], v[30:31] op_sel_hi:[0,1]
	v_pk_mul_f32 v[22:23], v[18:19], v[22:23]
	v_lshl_add_u64 v[30:31], v[34:35], 0, v[114:115]
	v_pk_mul_f32 v[18:19], v[36:37], v[24:25] op_sel_hi:[0,1]
	v_pk_mul_f32 v[24:25], v[20:21], v[18:19]
	v_cvt_pk_bf16_f32 v18, v26, v27
	v_cvt_pk_bf16_f32 v19, v28, v29
	v_cvt_pk_bf16_f32 v20, v22, v23
	v_cvt_pk_bf16_f32 v21, v24, v25
	global_store_dwordx4 v[30:31], v[18:21], off
	s_nop 1
	v_mul_f32_e32 v21, 0xbfb8aa3b, v149
	v_mul_f32_e32 v20, v14, v21
	v_exp_f32_e32 v22, v20
	v_mul_f32_e32 v20, v15, v21
	v_exp_f32_e32 v23, v20
	v_mul_f32_e32 v24, v16, v21
	v_mul_f32_e32 v25, v17, v21
	v_exp_f32_e32 v24, v24
	v_exp_f32_e32 v25, v25
	v_add_f32_e32 v22, 1.0, v22
	v_add_f32_e32 v23, 1.0, v23
	v_rcp_f32_e32 v22, v22
	v_rcp_f32_e32 v23, v23
	v_add_f32_e32 v16, 1.0, v24
	v_add_f32_e32 v17, 1.0, v25
	v_rcp_f32_e32 v16, v16
	v_rcp_f32_e32 v17, v17
	v_mul_f32_e32 v20, v149, v149
	v_pk_mul_f32 v[14:15], v[20:21], v[22:23] op_sel_hi:[0,1]
	v_pk_mul_f32 v[10:11], v[10:11], v[14:15]
	v_pk_mul_f32 v[14:15], v[20:21], v[16:17] op_sel_hi:[0,1]
	v_mul_f32_e32 v16, v6, v21
	v_mul_f32_e32 v17, v7, v21
	v_exp_f32_e32 v16, v16
	v_exp_f32_e32 v17, v17
	v_pk_mul_f32 v[12:13], v[12:13], v[14:15]
	v_mad_i64_i32 v[18:19], s[28:29], v148, s70, v[152:153]
	v_add_f32_e32 v14, 1.0, v16
	v_add_f32_e32 v15, 1.0, v17
	v_mul_f32_e32 v16, v8, v21
	v_mul_f32_e32 v17, v9, v21
	v_exp_f32_e32 v16, v16
	v_exp_f32_e32 v17, v17
	v_rcp_f32_e32 v14, v14
	v_rcp_f32_e32 v15, v15
	v_add_f32_e32 v8, 1.0, v16
	v_add_f32_e32 v9, 1.0, v17
	v_rcp_f32_e32 v8, v8
	v_rcp_f32_e32 v9, v9
	v_pk_mul_f32 v[6:7], v[20:21], v[14:15] op_sel_hi:[0,1]
	v_pk_mul_f32 v[6:7], v[2:3], v[6:7]
	v_lshl_add_u64 v[14:15], v[18:19], 0, v[114:115]
	v_pk_mul_f32 v[2:3], v[20:21], v[8:9] op_sel_hi:[0,1]
	v_pk_mul_f32 v[8:9], v[4:5], v[2:3]
	v_cvt_pk_bf16_f32 v2, v10, v11
	v_cvt_pk_bf16_f32 v3, v12, v13
	v_cvt_pk_bf16_f32 v4, v6, v7
	v_cvt_pk_bf16_f32 v5, v8, v9
	global_store_dwordx4 v[14:15], v[2:5], off
	s_cbranch_vccnz .LBB0_1929
	s_ashr_i32 s14, s14, 2
	s_cmp_lt_i32 s14, 4
	s_cbranch_scc1 .LBB0_1929
	s_waitcnt vmcnt(0)
	s_and_saveexec_b64 s[28:29], s[2:3]
	s_cbranch_execz .LBB0_1928
	s_mov_b64 s[30:31], exec
	v_mbcnt_lo_u32_b32 v2, s30, 0
	v_mbcnt_hi_u32_b32 v2, s31, v2
	v_cmp_eq_u32_e32 vcc, 0, v2
	s_and_b64 s[58:59], exec, vcc
	s_mov_b64 exec, s[58:59]
	s_cbranch_execz .LBB0_1928
	s_lshl_b32 s14, s14, 6
	s_addk_i32 s14, 0xff00
	s_lshl_b64 s[58:59], s[14:15], 2
	s_add_u32 s58, s38, s58
	s_addc_u32 s59, s39, s59
	s_bcnt1_i32_b64 s14, s[30:31]
	v_mov_b32_e32 v2, s14
	global_atomic_add v133, v2, s[58:59]
